# code placement: all 9 GEMM mainloop heads aligned to 64 bytes (.p2align 6)
# speedup vs baseline: 1.0031x; 1.0031x over previous
; template <class GEO, class Epi>
; __device__ __forceinline__ void gemm_phase(LAS unsigned char* lds, const Gemm g, const StaticOrder& S, const Epi& E) {
;     ...
; #pragma unroll
;     for (int a = 0; a < 2; ++a)
; #pragma unroll
;         for (int b = 0; b < 2; ++b)
; #pragma unroll
;             for (int m = 0; m < 4; ++m)
; #pragma unroll
;                 for (int n = 0; n < 2; ++n) acc[a][b][m][n] = (f32x4){0.f, 0.f, 0.f, 0.f};
;     ...
;         const bool has_next = S.next(ui + 1, nxt);
;         const char* nA = has_next ? PG8_APTR(nxt) : cA; const char* nB = has_next ? PG8_BPTR(nxt) : cB;
; #pragma nounroll
;         for (int t = 0; t < nt; t += 2) {
;             const bool last = (t == nt - 2);
;             const char* a1 = cA + (size_t)(t + 1) * kstep;
;             const char* a2 = last ? nA : cA + (size_t)(t + 2) * kstep; const char* b2 = last ? nB : cB + (size_t)(t + 2) * kstep;
;             const char* a3 = a2 + kstep; const char* b3 = b2 + kstep;
.LBB0_164:
	s_ashr_i32 s51, s50, 31
	s_lshl_b64 s[20:21], s[50:51], 19
	s_add_u32 s62, s96, s20
	s_addc_u32 s63, s97, s21
	s_and_b64 s[20:21], s[6:7], exec
	s_cselect_b32 s13, s63, s9
	s_cselect_b32 s20, s62, s8
	s_and_b32 s22, s84, 0x3fffffff
	s_lshl_b64 s[34:35], s[22:23], 19
	s_add_u32 s78, s36, s34
	s_addc_u32 s79, s37, s35
	s_and_b64 s[34:35], s[6:7], exec
	s_cselect_b32 s21, s79, s89
	s_cselect_b32 s22, s78, s88
	s_add_u32 s8, s8, 0x40080
	s_addc_u32 s9, s9, 0
	s_add_u32 s34, s88, 0x100
	v_mov_b32_e32 v32, 0
	s_addc_u32 s35, s89, 0
	s_mov_b32 s38, -2
	v_mov_b32_e32 v33, v32
	v_mov_b32_e32 v34, v32
	v_mov_b32_e32 v35, v32
	s_waitcnt vmcnt(0)
	v_mov_b32_e32 v36, v32
	v_mov_b32_e32 v37, v32
	v_mov_b32_e32 v38, v32
	v_mov_b32_e32 v39, v32
	v_mov_b32_e32 v72, v32
	v_mov_b32_e32 v73, v32
	v_mov_b32_e32 v74, v32
	v_mov_b32_e32 v75, v32
	v_mov_b32_e32 v76, v32
	v_mov_b32_e32 v77, v32
	v_mov_b32_e32 v78, v32
	v_mov_b32_e32 v79, v32
	v_mov_b32_e32 v80, v32
	v_mov_b32_e32 v81, v32
	v_mov_b32_e32 v82, v32
	v_mov_b32_e32 v83, v32
	v_mov_b32_e32 v84, v32
	v_mov_b32_e32 v85, v32
	v_mov_b32_e32 v86, v32
	v_mov_b32_e32 v87, v32
	v_mov_b32_e32 v88, v32
	v_mov_b32_e32 v89, v32
	v_mov_b32_e32 v90, v32
	v_mov_b32_e32 v91, v32
	v_mov_b32_e32 v92, v32
	v_mov_b32_e32 v93, v32
	v_mov_b32_e32 v94, v32
	v_mov_b32_e32 v95, v32
	v_mov_b32_e32 v0, v32
	v_mov_b32_e32 v1, v32
	v_mov_b32_e32 v2, v32
	v_mov_b32_e32 v3, v32
	v_mov_b32_e32 v4, v32
	v_mov_b32_e32 v5, v32
	v_mov_b32_e32 v6, v32
	v_mov_b32_e32 v7, v32
	v_mov_b32_e32 v8, v32
	v_mov_b32_e32 v9, v32
	v_mov_b32_e32 v10, v32
	v_mov_b32_e32 v11, v32
	v_mov_b32_e32 v12, v32
	v_mov_b32_e32 v13, v32
	v_mov_b32_e32 v14, v32
	v_mov_b32_e32 v15, v32
	v_mov_b32_e32 v16, v32
	v_mov_b32_e32 v17, v32
	v_mov_b32_e32 v18, v32
	v_mov_b32_e32 v19, v32
	v_mov_b32_e32 v20, v32
	v_mov_b32_e32 v21, v32
	v_mov_b32_e32 v22, v32
	v_mov_b32_e32 v23, v32
	v_mov_b32_e32 v24, v32
	v_mov_b32_e32 v25, v32
	v_mov_b32_e32 v26, v32
	v_mov_b32_e32 v27, v32
	v_mov_b32_e32 v28, v32
	v_mov_b32_e32 v29, v32
	v_mov_b32_e32 v30, v32
	v_mov_b32_e32 v31, v32
	v_mov_b32_e32 v96, v32
	v_mov_b32_e32 v97, v32
	v_mov_b32_e32 v98, v32
	v_mov_b32_e32 v99, v32
	v_mov_b32_e32 v100, v32
	v_mov_b32_e32 v101, v32
	v_mov_b32_e32 v102, v32
	v_mov_b32_e32 v103, v32
	v_mov_b32_e32 v104, v32
	v_mov_b32_e32 v105, v32
	v_mov_b32_e32 v106, v32
	v_mov_b32_e32 v107, v32
	v_mov_b32_e32 v108, v32
	v_mov_b32_e32 v109, v32
	v_mov_b32_e32 v110, v32
	v_mov_b32_e32 v111, v32
	v_mov_b32_e32 v112, v32
	v_mov_b32_e32 v113, v32
	v_mov_b32_e32 v114, v32
	v_mov_b32_e32 v115, v32
	v_mov_b32_e32 v116, v32
	v_mov_b32_e32 v117, v32
	v_mov_b32_e32 v118, v32
	v_mov_b32_e32 v119, v32
	v_mov_b32_e32 v128, v32
	v_mov_b32_e32 v129, v32
	v_mov_b32_e32 v130, v32
	v_mov_b32_e32 v131, v32
	v_mov_b32_e32 v132, v32
	v_mov_b32_e32 v133, v32
	v_mov_b32_e32 v134, v32
	v_mov_b32_e32 v135, v32
	v_mov_b32_e32 v40, v32
	v_mov_b32_e32 v41, v32
	v_mov_b32_e32 v42, v32
	v_mov_b32_e32 v43, v32
	v_mov_b32_e32 v44, v32
	v_mov_b32_e32 v45, v32
	v_mov_b32_e32 v46, v32
	v_mov_b32_e32 v47, v32
	v_mov_b32_e32 v48, v32
	v_mov_b32_e32 v49, v32
	v_mov_b32_e32 v50, v32
	v_mov_b32_e32 v51, v32
	v_mov_b32_e32 v52, v32
	v_mov_b32_e32 v53, v32
	v_mov_b32_e32 v54, v32
	v_mov_b32_e32 v55, v32
	v_mov_b32_e32 v56, v32
	v_mov_b32_e32 v57, v32
	v_mov_b32_e32 v58, v32
	v_mov_b32_e32 v59, v32
	v_mov_b32_e32 v60, v32
	v_mov_b32_e32 v61, v32
	v_mov_b32_e32 v62, v32
	v_mov_b32_e32 v63, v32
	v_mov_b32_e32 v64, v32
	v_mov_b32_e32 v65, v32
	v_mov_b32_e32 v66, v32
	v_mov_b32_e32 v67, v32
	v_mov_b32_e32 v68, v32
	v_mov_b32_e32 v69, v32
	v_mov_b32_e32 v70, v32
	v_mov_b32_e32 v71, v32
	.p2align 6

; template <class GEO, class Epi>
; __device__ __forceinline__ void gemm_phase(LAS unsigned char* lds, const Gemm g, const StaticOrder& S, const Epi& E) {
;     ...
; #pragma unroll
;     for (int a = 0; a < 2; ++a)
; #pragma unroll
;         for (int b = 0; b < 2; ++b)
; #pragma unroll
;             for (int m = 0; m < 4; ++m)
; #pragma unroll
;                 for (int n = 0; n < 2; ++n) acc[a][b][m][n] = (f32x4){0.f, 0.f, 0.f, 0.f};
;     ...
;         const bool has_next = S.next(ui + 1, nxt);
;         const char* nA = has_next ? PG8_APTR(nxt) : cA; const char* nB = has_next ? PG8_BPTR(nxt) : cB;
; #pragma nounroll
;         for (int t = 0; t < nt; t += 2) {
;             const bool last = (t == nt - 2);
;             const char* a1 = cA + (size_t)(t + 1) * kstep;
;             const char* a2 = last ? nA : cA + (size_t)(t + 2) * kstep; const char* b2 = last ? nB : cB + (size_t)(t + 2) * kstep;
;             const char* a3 = a2 + kstep; const char* b3 = b2 + kstep;
.LBB0_231:
	s_ashr_i32 s47, s46, 31
	s_lshl_b64 s[8:9], s[46:47], 19
	s_add_u32 s48, s58, s8
	s_addc_u32 s49, s59, s9
	s_and_b64 s[8:9], s[44:45], exec
	s_cselect_b32 s47, s49, s93
	s_cselect_b32 s52, s48, s92
	s_and_b32 s6, s56, 0x3fffffff
	s_lshl_b64 s[8:9], s[6:7], 19
	v_readlane_b32 s0, v254, 20
	v_readlane_b32 s1, v254, 21
	s_add_u32 s50, s0, s8
	s_addc_u32 s51, s1, s9
	s_and_b64 s[8:9], s[44:45], exec
	s_cselect_b32 s6, s51, s89
	s_cselect_b32 s53, s50, s88
	s_add_u32 s64, s92, 0x40080
	s_addc_u32 s65, s93, 0
	s_add_u32 s57, s88, 0x100
	v_mov_b32_e32 v0, 0
	s_addc_u32 vcc_lo, s89, 0
	s_mov_b32 vcc_hi, -2
	v_mov_b32_e32 v1, v0
	v_mov_b32_e32 v2, v0
	v_mov_b32_e32 v3, v0
	v_mov_b32_e32 v4, v0
	v_mov_b32_e32 v5, v0
	v_mov_b32_e32 v6, v0
	v_mov_b32_e32 v7, v0
	v_mov_b32_e32 v8, v0
	v_mov_b32_e32 v9, v0
	v_mov_b32_e32 v10, v0
	v_mov_b32_e32 v11, v0
	v_mov_b32_e32 v12, v0
	v_mov_b32_e32 v13, v0
	v_mov_b32_e32 v14, v0
	v_mov_b32_e32 v15, v0
	v_mov_b32_e32 v24, v0
	v_mov_b32_e32 v25, v0
	v_mov_b32_e32 v26, v0
	v_mov_b32_e32 v27, v0
	s_waitcnt vmcnt(0)
	v_mov_b32_e32 v28, v0
	v_mov_b32_e32 v29, v0
	v_mov_b32_e32 v30, v0
	v_mov_b32_e32 v31, v0
	v_mov_b32_e32 v40, v0
	v_mov_b32_e32 v41, v0
	v_mov_b32_e32 v42, v0
	v_mov_b32_e32 v43, v0
	v_mov_b32_e32 v44, v0
	v_mov_b32_e32 v45, v0
	v_mov_b32_e32 v46, v0
	v_mov_b32_e32 v47, v0
	v_mov_b32_e32 v16, v0
	v_mov_b32_e32 v17, v0
	v_mov_b32_e32 v18, v0
	v_mov_b32_e32 v19, v0
	v_mov_b32_e32 v20, v0
	v_mov_b32_e32 v21, v0
	v_mov_b32_e32 v22, v0
	v_mov_b32_e32 v23, v0
	v_mov_b32_e32 v32, v0
	v_mov_b32_e32 v33, v0
	v_mov_b32_e32 v34, v0
	v_mov_b32_e32 v35, v0
	v_mov_b32_e32 v36, v0
	v_mov_b32_e32 v37, v0
	v_mov_b32_e32 v38, v0
	v_mov_b32_e32 v39, v0
	v_mov_b32_e32 v48, v0
	v_mov_b32_e32 v49, v0
	v_mov_b32_e32 v50, v0
	v_mov_b32_e32 v51, v0
	v_mov_b32_e32 v52, v0
	v_mov_b32_e32 v53, v0
	v_mov_b32_e32 v54, v0
	v_mov_b32_e32 v55, v0
	v_mov_b32_e32 v56, v0
	v_mov_b32_e32 v57, v0
	v_mov_b32_e32 v58, v0
	v_mov_b32_e32 v59, v0
	v_mov_b32_e32 v60, v0
	v_mov_b32_e32 v61, v0
	v_mov_b32_e32 v62, v0
	v_mov_b32_e32 v63, v0
	v_mov_b32_e32 v64, v0
	v_mov_b32_e32 v65, v0
	v_mov_b32_e32 v66, v0
	v_mov_b32_e32 v67, v0
	v_mov_b32_e32 v68, v0
	v_mov_b32_e32 v69, v0
	v_mov_b32_e32 v70, v0
	v_mov_b32_e32 v71, v0
	v_mov_b32_e32 v72, v0
	v_mov_b32_e32 v73, v0
	v_mov_b32_e32 v74, v0
	v_mov_b32_e32 v75, v0
	v_mov_b32_e32 v76, v0
	v_mov_b32_e32 v77, v0
	v_mov_b32_e32 v78, v0
	v_mov_b32_e32 v79, v0
	v_mov_b32_e32 v88, v0
	v_mov_b32_e32 v89, v0
	v_mov_b32_e32 v90, v0
	v_mov_b32_e32 v91, v0
	v_mov_b32_e32 v92, v0
	v_mov_b32_e32 v93, v0
	v_mov_b32_e32 v94, v0
	v_mov_b32_e32 v95, v0
	v_mov_b32_e32 v104, v0
	v_mov_b32_e32 v105, v0
	v_mov_b32_e32 v106, v0
	v_mov_b32_e32 v107, v0
	v_mov_b32_e32 v108, v0
	v_mov_b32_e32 v109, v0
	v_mov_b32_e32 v110, v0
	v_mov_b32_e32 v111, v0
	v_mov_b32_e32 v80, v0
	v_mov_b32_e32 v81, v0
	v_mov_b32_e32 v82, v0
	v_mov_b32_e32 v83, v0
	v_mov_b32_e32 v84, v0
	v_mov_b32_e32 v85, v0
	v_mov_b32_e32 v86, v0
	v_mov_b32_e32 v87, v0
	v_mov_b32_e32 v96, v0
	v_mov_b32_e32 v97, v0
	v_mov_b32_e32 v98, v0
	v_mov_b32_e32 v99, v0
	v_mov_b32_e32 v100, v0
	v_mov_b32_e32 v101, v0
	v_mov_b32_e32 v102, v0
	v_mov_b32_e32 v103, v0
	v_mov_b32_e32 v112, v0
	v_mov_b32_e32 v113, v0
	v_mov_b32_e32 v114, v0
	v_mov_b32_e32 v115, v0
	v_mov_b32_e32 v116, v0
	v_mov_b32_e32 v117, v0
	v_mov_b32_e32 v118, v0
	v_mov_b32_e32 v119, v0
	v_mov_b32_e32 v120, v0
	v_mov_b32_e32 v121, v0
	v_mov_b32_e32 v122, v0
	v_mov_b32_e32 v123, v0
	v_mov_b32_e32 v124, v0
	v_mov_b32_e32 v125, v0
	v_mov_b32_e32 v126, v0
	v_mov_b32_e32 v127, v0
	.p2align 6

; template <class GEO, class Epi>
; __device__ __forceinline__ void gemm_phase(LAS unsigned char* lds, const Gemm g, const StaticOrder& S, const Epi& E) {
;     ...
; #pragma unroll
;     for (int a = 0; a < 2; ++a)
; #pragma unroll
;         for (int b = 0; b < 2; ++b)
; #pragma unroll
;             for (int m = 0; m < 4; ++m)
; #pragma unroll
;                 for (int n = 0; n < 2; ++n) acc[a][b][m][n] = (f32x4){0.f, 0.f, 0.f, 0.f};
;     ...
;         const bool has_next = S.next(ui + 1, nxt);
;         const char* nA = has_next ? PG8_APTR(nxt) : cA; const char* nB = has_next ? PG8_BPTR(nxt) : cB;
; #pragma nounroll
;         for (int t = 0; t < nt; t += 2) {
;             const bool last = (t == nt - 2);
;             const char* a1 = cA + (size_t)(t + 1) * kstep;
;             const char* a2 = last ? nA : cA + (size_t)(t + 2) * kstep; const char* b2 = last ? nB : cB + (size_t)(t + 2) * kstep;
;             const char* a3 = a2 + kstep; const char* b3 = b2 + kstep;
.LBB0_424:
	s_ashr_i32 s45, s44, 31
	s_lshl_b32 s8, s37, 9
	s_and_b32 s50, s8, 0x600
	s_lshl_b64 s[8:9], s[44:45], 19
	v_readlane_b32 s48, v254, 33
	v_readlane_b32 s49, v254, 34
	s_add_u32 s8, s48, s8
	s_addc_u32 s9, s49, s9
	s_add_u32 s48, s8, s50
	s_addc_u32 s49, s9, 0
	s_and_b64 s[8:9], s[42:43], exec
	s_cselect_b32 s39, s49, s47
	s_cselect_b32 s45, s48, s46
	s_ashr_i32 s8, s37, 2
	s_ashr_i32 s9, s8, 31
	s_lshl_b64 s[8:9], s[8:9], 19
	s_add_u32 s8, s62, s8
	s_addc_u32 s9, s63, s9
	s_add_u32 s50, s8, s50
	s_addc_u32 s51, s9, 0
	s_and_b64 s[8:9], s[42:43], exec
	v_mov_b32_e32 v0, 0
	s_cselect_b32 s52, s51, s41
	s_cselect_b32 s53, s50, s40
	s_mov_b64 s[64:65], 0
	s_mov_b64 s[58:59], -1
	s_mov_b64 s[60:61], 0
	v_mov_b32_e32 v1, v0
	v_mov_b32_e32 v2, v0
	v_mov_b32_e32 v3, v0
	v_mov_b32_e32 v4, v0
	v_mov_b32_e32 v5, v0
	v_mov_b32_e32 v6, v0
	v_mov_b32_e32 v7, v0
	v_mov_b32_e32 v8, v0
	v_mov_b32_e32 v9, v0
	v_mov_b32_e32 v10, v0
	v_mov_b32_e32 v11, v0
	v_mov_b32_e32 v12, v0
	v_mov_b32_e32 v13, v0
	v_mov_b32_e32 v14, v0
	v_mov_b32_e32 v15, v0
	v_mov_b32_e32 v24, v0
	v_mov_b32_e32 v25, v0
	v_mov_b32_e32 v26, v0
	v_mov_b32_e32 v27, v0
	v_mov_b32_e32 v28, v0
	v_mov_b32_e32 v29, v0
	v_mov_b32_e32 v30, v0
	v_mov_b32_e32 v31, v0
	v_mov_b32_e32 v40, v0
	v_mov_b32_e32 v41, v0
	v_mov_b32_e32 v42, v0
	v_mov_b32_e32 v43, v0
	v_mov_b32_e32 v44, v0
	v_mov_b32_e32 v45, v0
	v_mov_b32_e32 v46, v0
	v_mov_b32_e32 v47, v0
	v_mov_b32_e32 v16, v0
	v_mov_b32_e32 v17, v0
	v_mov_b32_e32 v18, v0
	v_mov_b32_e32 v19, v0
	v_mov_b32_e32 v20, v0
	v_mov_b32_e32 v21, v0
	v_mov_b32_e32 v22, v0
	v_mov_b32_e32 v23, v0
	v_mov_b32_e32 v32, v0
	v_mov_b32_e32 v33, v0
	v_mov_b32_e32 v34, v0
	v_mov_b32_e32 v35, v0
	v_mov_b32_e32 v36, v0
	v_mov_b32_e32 v37, v0
	v_mov_b32_e32 v38, v0
	v_mov_b32_e32 v39, v0
	v_mov_b32_e32 v48, v0
	v_mov_b32_e32 v49, v0
	v_mov_b32_e32 v50, v0
	v_mov_b32_e32 v51, v0
	v_mov_b32_e32 v52, v0
	v_mov_b32_e32 v53, v0
	v_mov_b32_e32 v54, v0
	v_mov_b32_e32 v55, v0
	v_mov_b32_e32 v56, v0
	v_mov_b32_e32 v57, v0
	v_mov_b32_e32 v58, v0
	v_mov_b32_e32 v59, v0
	v_mov_b32_e32 v60, v0
	v_mov_b32_e32 v61, v0
	v_mov_b32_e32 v62, v0
	v_mov_b32_e32 v63, v0
	v_mov_b32_e32 v64, v0
	v_mov_b32_e32 v65, v0
	v_mov_b32_e32 v66, v0
	v_mov_b32_e32 v67, v0
	v_mov_b32_e32 v68, v0
	v_mov_b32_e32 v69, v0
	v_mov_b32_e32 v70, v0
	v_mov_b32_e32 v71, v0
	v_mov_b32_e32 v72, v0
	v_mov_b32_e32 v73, v0
	v_mov_b32_e32 v74, v0
	v_mov_b32_e32 v75, v0
	v_mov_b32_e32 v76, v0
	v_mov_b32_e32 v77, v0
	v_mov_b32_e32 v78, v0
	v_mov_b32_e32 v79, v0
	v_mov_b32_e32 v88, v0
	v_mov_b32_e32 v89, v0
	v_mov_b32_e32 v90, v0
	v_mov_b32_e32 v91, v0
	v_mov_b32_e32 v92, v0
	v_mov_b32_e32 v93, v0
	v_mov_b32_e32 v94, v0
	v_mov_b32_e32 v95, v0
	v_mov_b32_e32 v104, v0
	v_mov_b32_e32 v105, v0
	v_mov_b32_e32 v106, v0
	v_mov_b32_e32 v107, v0
	v_mov_b32_e32 v108, v0
	v_mov_b32_e32 v109, v0
	v_mov_b32_e32 v110, v0
	v_mov_b32_e32 v111, v0
	v_mov_b32_e32 v80, v0
	v_mov_b32_e32 v81, v0
	v_mov_b32_e32 v82, v0
	v_mov_b32_e32 v83, v0
	v_mov_b32_e32 v84, v0
	v_mov_b32_e32 v85, v0
	v_mov_b32_e32 v86, v0
	v_mov_b32_e32 v87, v0
	v_mov_b32_e32 v96, v0
	v_mov_b32_e32 v97, v0
	v_mov_b32_e32 v98, v0
	v_mov_b32_e32 v99, v0
	v_mov_b32_e32 v100, v0
	v_mov_b32_e32 v101, v0
	v_mov_b32_e32 v102, v0
	v_mov_b32_e32 v103, v0
	v_mov_b32_e32 v112, v0
	v_mov_b32_e32 v113, v0
	v_mov_b32_e32 v114, v0
	v_mov_b32_e32 v115, v0
	v_mov_b32_e32 v116, v0
	v_mov_b32_e32 v117, v0
	v_mov_b32_e32 v118, v0
	v_mov_b32_e32 v119, v0
	v_mov_b32_e32 v120, v0
	v_mov_b32_e32 v121, v0
	v_mov_b32_e32 v122, v0
	v_mov_b32_e32 v123, v0
	v_mov_b32_e32 v124, v0
	v_mov_b32_e32 v125, v0
	v_mov_b32_e32 v126, v0
	v_mov_b32_e32 v127, v0
	.p2align 6

; template <class GEO, class Epi>
; __device__ __forceinline__ void gemm_phase(LAS unsigned char* lds, const Gemm g, const StaticOrder& S, const Epi& E) {
;     ...
; #pragma unroll
;     for (int a = 0; a < 2; ++a)
; #pragma unroll
;         for (int b = 0; b < 2; ++b)
; #pragma unroll
;             for (int m = 0; m < 4; ++m)
; #pragma unroll
;                 for (int n = 0; n < 2; ++n) acc[a][b][m][n] = (f32x4){0.f, 0.f, 0.f, 0.f};
;     ...
;         const bool has_next = S.next(ui + 1, nxt);
;         const char* nA = has_next ? PG8_APTR(nxt) : cA; const char* nB = has_next ? PG8_BPTR(nxt) : cB;
; #pragma nounroll
;         for (int t = 0; t < nt; t += 2) {
;             const bool last = (t == nt - 2);
;             const char* a1 = cA + (size_t)(t + 1) * kstep;
;             const char* a2 = last ? nA : cA + (size_t)(t + 2) * kstep; const char* b2 = last ? nB : cB + (size_t)(t + 2) * kstep;
;             const char* a3 = a2 + kstep; const char* b3 = b2 + kstep;
.LBB0_690:
	s_ashr_i32 s47, s46, 31
	s_lshl_b64 s[8:9], s[46:47], 19
	s_add_u32 s48, s83, s8
	s_addc_u32 s49, s88, s9
	s_and_b64 s[8:9], s[44:45], exec
	s_cselect_b32 s21, s49, s55
	s_cselect_b32 s47, s48, s54
	s_and_b32 s22, s66, 0x3fffffff
	s_lshl_b64 s[8:9], s[22:23], 19
	v_readlane_b32 s38, v254, 35
	v_readlane_b32 s39, v254, 36
	s_add_u32 s50, s38, s8
	s_addc_u32 s51, s39, s9
	s_and_b64 s[8:9], s[44:45], exec
	s_cselect_b32 s22, s51, s57
	s_cselect_b32 s53, s50, s56
	s_add_u32 s54, s54, 0x40080
	s_addc_u32 s55, s55, 0
	s_add_u32 s67, s56, 0x100
	v_mov_b32_e32 v0, 0
	s_addc_u32 s68, s57, 0
	s_mov_b32 s69, -2
	s_waitcnt lgkmcnt(0)
	v_mov_b32_e32 v1, v0
	v_mov_b32_e32 v2, v0
	v_mov_b32_e32 v3, v0
	v_mov_b32_e32 v4, v0
	v_mov_b32_e32 v5, v0
	v_mov_b32_e32 v6, v0
	v_mov_b32_e32 v7, v0
	v_mov_b32_e32 v16, v0
	v_mov_b32_e32 v17, v0
	v_mov_b32_e32 v18, v0
	v_mov_b32_e32 v19, v0
	v_mov_b32_e32 v20, v0
	v_mov_b32_e32 v21, v0
	v_mov_b32_e32 v22, v0
	v_mov_b32_e32 v23, v0
	v_mov_b32_e32 v32, v0
	v_mov_b32_e32 v33, v0
	v_mov_b32_e32 v34, v0
	v_mov_b32_e32 v35, v0
	v_mov_b32_e32 v36, v0
	v_mov_b32_e32 v37, v0
	v_mov_b32_e32 v38, v0
	v_mov_b32_e32 v39, v0
	v_mov_b32_e32 v48, v0
	v_mov_b32_e32 v49, v0
	v_mov_b32_e32 v50, v0
	v_mov_b32_e32 v51, v0
	v_mov_b32_e32 v52, v0
	v_mov_b32_e32 v53, v0
	v_mov_b32_e32 v54, v0
	v_mov_b32_e32 v55, v0
	v_mov_b32_e32 v8, v0
	v_mov_b32_e32 v9, v0
	v_mov_b32_e32 v10, v0
	v_mov_b32_e32 v11, v0
	v_mov_b32_e32 v12, v0
	v_mov_b32_e32 v13, v0
	v_mov_b32_e32 v14, v0
	v_mov_b32_e32 v15, v0
	v_mov_b32_e32 v24, v0
	v_mov_b32_e32 v25, v0
	v_mov_b32_e32 v26, v0
	v_mov_b32_e32 v27, v0
	v_mov_b32_e32 v28, v0
	v_mov_b32_e32 v29, v0
	v_mov_b32_e32 v30, v0
	v_mov_b32_e32 v31, v0
	v_mov_b32_e32 v40, v0
	v_mov_b32_e32 v41, v0
	v_mov_b32_e32 v42, v0
	v_mov_b32_e32 v43, v0
	v_mov_b32_e32 v44, v0
	v_mov_b32_e32 v45, v0
	v_mov_b32_e32 v46, v0
	v_mov_b32_e32 v47, v0
	v_mov_b32_e32 v56, v0
	v_mov_b32_e32 v57, v0
	v_mov_b32_e32 v58, v0
	v_mov_b32_e32 v59, v0
	v_mov_b32_e32 v60, v0
	v_mov_b32_e32 v61, v0
	v_mov_b32_e32 v62, v0
	v_mov_b32_e32 v63, v0
	v_mov_b32_e32 v64, v0
	v_mov_b32_e32 v65, v0
	v_mov_b32_e32 v66, v0
	v_mov_b32_e32 v67, v0
	v_mov_b32_e32 v68, v0
	v_mov_b32_e32 v69, v0
	v_mov_b32_e32 v70, v0
	v_mov_b32_e32 v71, v0
	v_mov_b32_e32 v80, v0
	v_mov_b32_e32 v81, v0
	v_mov_b32_e32 v82, v0
	v_mov_b32_e32 v83, v0
	v_mov_b32_e32 v84, v0
	v_mov_b32_e32 v85, v0
	v_mov_b32_e32 v86, v0
	v_mov_b32_e32 v87, v0
	v_mov_b32_e32 v96, v0
	v_mov_b32_e32 v97, v0
	s_waitcnt vmcnt(0)
	v_mov_b32_e32 v98, v0
	v_mov_b32_e32 v99, v0
	v_mov_b32_e32 v100, v0
	v_mov_b32_e32 v101, v0
	v_mov_b32_e32 v102, v0
	v_mov_b32_e32 v103, v0
	v_mov_b32_e32 v112, v0
	v_mov_b32_e32 v113, v0
	v_mov_b32_e32 v114, v0
	v_mov_b32_e32 v115, v0
	v_mov_b32_e32 v116, v0
	v_mov_b32_e32 v117, v0
	v_mov_b32_e32 v118, v0
	v_mov_b32_e32 v119, v0
	v_mov_b32_e32 v72, v0
	v_mov_b32_e32 v73, v0
	v_mov_b32_e32 v74, v0
	v_mov_b32_e32 v75, v0
	v_mov_b32_e32 v76, v0
	v_mov_b32_e32 v77, v0
	v_mov_b32_e32 v78, v0
	v_mov_b32_e32 v79, v0
	v_mov_b32_e32 v88, v0
	v_mov_b32_e32 v89, v0
	v_mov_b32_e32 v90, v0
	v_mov_b32_e32 v91, v0
	v_mov_b32_e32 v92, v0
	v_mov_b32_e32 v93, v0
	v_mov_b32_e32 v94, v0
	v_mov_b32_e32 v95, v0
	v_mov_b32_e32 v104, v0
	v_mov_b32_e32 v105, v0
	v_mov_b32_e32 v106, v0
	v_mov_b32_e32 v107, v0
	v_mov_b32_e32 v108, v0
	v_mov_b32_e32 v109, v0
	v_mov_b32_e32 v110, v0
	v_mov_b32_e32 v111, v0
	v_mov_b32_e32 v120, v0
	v_mov_b32_e32 v121, v0
	v_mov_b32_e32 v122, v0
	v_mov_b32_e32 v123, v0
	v_mov_b32_e32 v124, v0
	v_mov_b32_e32 v125, v0
	v_mov_b32_e32 v126, v0
	v_mov_b32_e32 v127, v0
	.p2align 6

; template <class GEO, class Epi>
; __device__ __forceinline__ void gemm_phase(LAS unsigned char* lds, const Gemm g, const StaticOrder& S, const Epi& E) {
;     ...
; #pragma unroll
;     for (int a = 0; a < 2; ++a)
; #pragma unroll
;         for (int b = 0; b < 2; ++b)
; #pragma unroll
;             for (int m = 0; m < 4; ++m)
; #pragma unroll
;                 for (int n = 0; n < 2; ++n) acc[a][b][m][n] = (f32x4){0.f, 0.f, 0.f, 0.f};
;     ...
;         const bool has_next = S.next(ui + 1, nxt);
;         const char* nA = has_next ? PG8_APTR(nxt) : cA; const char* nB = has_next ? PG8_BPTR(nxt) : cB;
; #pragma nounroll
;         for (int t = 0; t < nt; t += 2) {
;             const bool last = (t == nt - 2);
;             const char* a1 = cA + (size_t)(t + 1) * kstep;
;             const char* a2 = last ? nA : cA + (size_t)(t + 2) * kstep; const char* b2 = last ? nB : cB + (size_t)(t + 2) * kstep;
;             const char* a3 = a2 + kstep; const char* b3 = b2 + kstep;
.LBB0_778:
	s_ashr_i32 s47, s46, 31
	s_lshl_b64 s[8:9], s[46:47], 19
	s_add_u32 s48, s26, s8
	v_cmp_lt_i64_e64 s[42:43], s[42:43], v[144:145]
	s_addc_u32 s49, s27, s9
	s_and_b64 s[8:9], s[42:43], exec
	s_cselect_b32 s45, s49, s53
	s_cselect_b32 s47, s48, s52
	s_and_b32 s16, s64, 0x3fffffff
	s_lshl_b64 s[8:9], s[16:17], 19
	s_add_u32 s50, s70, s8
	s_addc_u32 s51, s71, s9
	s_and_b64 s[8:9], s[42:43], exec
	s_cselect_b32 s16, s51, s55
	s_cselect_b32 s66, s50, s54
	s_add_u32 s52, s52, 0x40080
	s_addc_u32 s53, s53, 0
	s_add_u32 s67, s54, 0x100
	v_mov_b32_e32 v0, 0
	s_addc_u32 s68, s55, 0
	s_mov_b32 s69, -2
	v_mov_b32_e32 v1, v0
	v_mov_b32_e32 v2, v0
	v_mov_b32_e32 v3, v0
	v_mov_b32_e32 v4, v0
	v_mov_b32_e32 v5, v0
	v_mov_b32_e32 v6, v0
	v_mov_b32_e32 v7, v0
	v_mov_b32_e32 v12, v0
	v_mov_b32_e32 v13, v0
	v_mov_b32_e32 v14, v0
	v_mov_b32_e32 v15, v0
	v_mov_b32_e32 v20, v0
	v_mov_b32_e32 v21, v0
	v_mov_b32_e32 v22, v0
	v_mov_b32_e32 v23, v0
	v_mov_b32_e32 v28, v0
	v_mov_b32_e32 v29, v0
	v_mov_b32_e32 v30, v0
	v_mov_b32_e32 v31, v0
	v_mov_b32_e32 v36, v0
	v_mov_b32_e32 v37, v0
	v_mov_b32_e32 v38, v0
	v_mov_b32_e32 v39, v0
	v_mov_b32_e32 v44, v0
	v_mov_b32_e32 v45, v0
	v_mov_b32_e32 v46, v0
	v_mov_b32_e32 v47, v0
	v_mov_b32_e32 v52, v0
	v_mov_b32_e32 v53, v0
	v_mov_b32_e32 v54, v0
	v_mov_b32_e32 v55, v0
	v_mov_b32_e32 v8, v0
	v_mov_b32_e32 v9, v0
	v_mov_b32_e32 v10, v0
	v_mov_b32_e32 v11, v0
	v_mov_b32_e32 v16, v0
	v_mov_b32_e32 v17, v0
	v_mov_b32_e32 v18, v0
	v_mov_b32_e32 v19, v0
	v_mov_b32_e32 v24, v0
	v_mov_b32_e32 v25, v0
	v_mov_b32_e32 v26, v0
	v_mov_b32_e32 v27, v0
	v_mov_b32_e32 v32, v0
	v_mov_b32_e32 v33, v0
	v_mov_b32_e32 v34, v0
	v_mov_b32_e32 v35, v0
	v_mov_b32_e32 v40, v0
	v_mov_b32_e32 v41, v0
	v_mov_b32_e32 v42, v0
	v_mov_b32_e32 v43, v0
	v_mov_b32_e32 v48, v0
	v_mov_b32_e32 v49, v0
	v_mov_b32_e32 v50, v0
	v_mov_b32_e32 v51, v0
	v_mov_b32_e32 v56, v0
	v_mov_b32_e32 v57, v0
	v_mov_b32_e32 v58, v0
	v_mov_b32_e32 v59, v0
	v_mov_b32_e32 v60, v0
	v_mov_b32_e32 v61, v0
	v_mov_b32_e32 v62, v0
	v_mov_b32_e32 v63, v0
	v_mov_b32_e32 v64, v0
	v_mov_b32_e32 v65, v0
	v_mov_b32_e32 v66, v0
	v_mov_b32_e32 v67, v0
	v_mov_b32_e32 v68, v0
	v_mov_b32_e32 v69, v0
	v_mov_b32_e32 v70, v0
	v_mov_b32_e32 v71, v0
	v_mov_b32_e32 v76, v0
	v_mov_b32_e32 v77, v0
	v_mov_b32_e32 v78, v0
	v_mov_b32_e32 v79, v0
	v_mov_b32_e32 v84, v0
	v_mov_b32_e32 v85, v0
	v_mov_b32_e32 v86, v0
	v_mov_b32_e32 v87, v0
	v_mov_b32_e32 v92, v0
	v_mov_b32_e32 v93, v0
	v_mov_b32_e32 v94, v0
	v_mov_b32_e32 v95, v0
	s_waitcnt vmcnt(0)
	v_mov_b32_e32 v100, v0
	v_mov_b32_e32 v101, v0
	v_mov_b32_e32 v102, v0
	v_mov_b32_e32 v103, v0
	v_mov_b32_e32 v108, v0
	v_mov_b32_e32 v109, v0
	v_mov_b32_e32 v110, v0
	v_mov_b32_e32 v111, v0
	v_mov_b32_e32 v116, v0
	v_mov_b32_e32 v117, v0
	v_mov_b32_e32 v118, v0
	v_mov_b32_e32 v119, v0
	v_mov_b32_e32 v72, v0
	v_mov_b32_e32 v73, v0
	v_mov_b32_e32 v74, v0
	v_mov_b32_e32 v75, v0
	v_mov_b32_e32 v80, v0
	v_mov_b32_e32 v81, v0
	v_mov_b32_e32 v82, v0
	v_mov_b32_e32 v83, v0
	v_mov_b32_e32 v88, v0
	v_mov_b32_e32 v89, v0
	v_mov_b32_e32 v90, v0
	v_mov_b32_e32 v91, v0
	v_mov_b32_e32 v96, v0
	v_mov_b32_e32 v97, v0
	v_mov_b32_e32 v98, v0
	v_mov_b32_e32 v99, v0
	v_mov_b32_e32 v104, v0
	v_mov_b32_e32 v105, v0
	v_mov_b32_e32 v106, v0
	v_mov_b32_e32 v107, v0
	v_mov_b32_e32 v112, v0
	v_mov_b32_e32 v113, v0
	v_mov_b32_e32 v114, v0
	v_mov_b32_e32 v115, v0
	v_mov_b32_e32 v120, v0
	v_mov_b32_e32 v121, v0
	v_mov_b32_e32 v122, v0
	v_mov_b32_e32 v123, v0
	v_mov_b32_e32 v124, v0
	v_mov_b32_e32 v125, v0
	v_mov_b32_e32 v126, v0
	v_mov_b32_e32 v127, v0
	.p2align 6

; template <class GEO, class Epi>
; __device__ __forceinline__ void gemm_phase(LAS unsigned char* lds, const Gemm g, const StaticOrder& S, const Epi& E) {
;     ...
; #pragma unroll
;     for (int a = 0; a < 2; ++a)
; #pragma unroll
;         for (int b = 0; b < 2; ++b)
; #pragma unroll
;             for (int m = 0; m < 4; ++m)
; #pragma unroll
;                 for (int n = 0; n < 2; ++n) acc[a][b][m][n] = (f32x4){0.f, 0.f, 0.f, 0.f};
;     ...
;         const bool has_next = S.next(ui + 1, nxt);
;         const char* nA = has_next ? PG8_APTR(nxt) : cA; const char* nB = has_next ? PG8_BPTR(nxt) : cB;
; #pragma nounroll
;         for (int t = 0; t < nt; t += 2) {
;             const bool last = (t == nt - 2);
;             const char* a1 = cA + (size_t)(t + 1) * kstep;
;             const char* a2 = last ? nA : cA + (size_t)(t + 2) * kstep; const char* b2 = last ? nB : cB + (size_t)(t + 2) * kstep;
;             const char* a3 = a2 + kstep; const char* b3 = b2 + kstep;
.LBB0_881:
	s_ashr_i32 s45, s44, 31
	s_and_b32 s20, s89, 0x3fffffff
	s_lshl_b64 s[8:9], s[20:21], 9
	s_lshl_b64 s[38:39], s[44:45], 19
	s_add_u32 s20, s14, s38
	s_addc_u32 s38, s15, s39
	s_add_u32 s46, s20, s8
	s_addc_u32 s47, s38, s9
	s_and_b64 s[38:39], s[42:43], exec
	s_cselect_b32 s20, s47, s55
	s_cselect_b32 s45, s46, s54
	s_ashr_i32 s38, s44, 5
	s_ashr_i32 s39, s38, 31
	s_lshl_b64 s[38:39], s[38:39], 19
	v_readlane_b32 s48, v253, 51
	v_readlane_b32 s49, v253, 52
	s_add_u32 s8, s48, s8
	s_addc_u32 s9, s49, s9
	s_add_u32 s48, s8, s38
	s_addc_u32 s49, s9, s39
	s_and_b64 s[8:9], s[42:43], exec
	v_mov_b32_e32 v0, 0
	s_cselect_b32 s51, s49, s53
	s_cselect_b32 s91, s48, s52
	s_mov_b64 s[60:61], 0
	s_mov_b64 s[56:57], -1
	s_mov_b64 s[58:59], 0
	v_mov_b32_e32 v1, v0
	v_mov_b32_e32 v2, v0
	v_mov_b32_e32 v3, v0
	v_mov_b32_e32 v4, v0
	v_mov_b32_e32 v5, v0
	v_mov_b32_e32 v6, v0
	v_mov_b32_e32 v7, v0
	v_mov_b32_e32 v16, v0
	v_mov_b32_e32 v17, v0
	v_mov_b32_e32 v18, v0
	v_mov_b32_e32 v19, v0
	v_mov_b32_e32 v20, v0
	v_mov_b32_e32 v21, v0
	v_mov_b32_e32 v22, v0
	v_mov_b32_e32 v23, v0
	v_mov_b32_e32 v32, v0
	v_mov_b32_e32 v33, v0
	v_mov_b32_e32 v34, v0
	v_mov_b32_e32 v35, v0
	v_mov_b32_e32 v36, v0
	v_mov_b32_e32 v37, v0
	v_mov_b32_e32 v38, v0
	v_mov_b32_e32 v39, v0
	v_mov_b32_e32 v48, v0
	v_mov_b32_e32 v49, v0
	v_mov_b32_e32 v50, v0
	v_mov_b32_e32 v51, v0
	v_mov_b32_e32 v52, v0
	v_mov_b32_e32 v53, v0
	v_mov_b32_e32 v54, v0
	v_mov_b32_e32 v55, v0
	v_mov_b32_e32 v8, v0
	v_mov_b32_e32 v9, v0
	v_mov_b32_e32 v10, v0
	v_mov_b32_e32 v11, v0
	v_mov_b32_e32 v12, v0
	v_mov_b32_e32 v13, v0
	v_mov_b32_e32 v14, v0
	v_mov_b32_e32 v15, v0
	v_mov_b32_e32 v24, v0
	v_mov_b32_e32 v25, v0
	v_mov_b32_e32 v26, v0
	v_mov_b32_e32 v27, v0
	v_mov_b32_e32 v28, v0
	v_mov_b32_e32 v29, v0
	v_mov_b32_e32 v30, v0
	v_mov_b32_e32 v31, v0
	v_mov_b32_e32 v40, v0
	v_mov_b32_e32 v41, v0
	v_mov_b32_e32 v42, v0
	v_mov_b32_e32 v43, v0
	v_mov_b32_e32 v44, v0
	v_mov_b32_e32 v45, v0
	v_mov_b32_e32 v46, v0
	v_mov_b32_e32 v47, v0
	v_mov_b32_e32 v56, v0
	v_mov_b32_e32 v57, v0
	v_mov_b32_e32 v58, v0
	v_mov_b32_e32 v59, v0
	v_mov_b32_e32 v60, v0
	v_mov_b32_e32 v61, v0
	v_mov_b32_e32 v62, v0
	v_mov_b32_e32 v63, v0
	v_mov_b32_e32 v64, v0
	v_mov_b32_e32 v65, v0
	v_mov_b32_e32 v66, v0
	v_mov_b32_e32 v67, v0
	v_mov_b32_e32 v68, v0
	v_mov_b32_e32 v69, v0
	v_mov_b32_e32 v70, v0
	v_mov_b32_e32 v71, v0
	v_mov_b32_e32 v80, v0
	v_mov_b32_e32 v81, v0
	v_mov_b32_e32 v82, v0
	v_mov_b32_e32 v83, v0
	v_mov_b32_e32 v84, v0
	v_mov_b32_e32 v85, v0
	v_mov_b32_e32 v86, v0
	v_mov_b32_e32 v87, v0
	v_mov_b32_e32 v96, v0
	v_mov_b32_e32 v97, v0
	v_mov_b32_e32 v98, v0
	v_mov_b32_e32 v99, v0
	v_mov_b32_e32 v100, v0
	v_mov_b32_e32 v101, v0
	v_mov_b32_e32 v102, v0
	v_mov_b32_e32 v103, v0
	v_mov_b32_e32 v112, v0
	v_mov_b32_e32 v113, v0
	v_mov_b32_e32 v114, v0
	v_mov_b32_e32 v115, v0
	v_mov_b32_e32 v116, v0
	v_mov_b32_e32 v117, v0
	v_mov_b32_e32 v118, v0
	v_mov_b32_e32 v119, v0
	v_mov_b32_e32 v72, v0
	v_mov_b32_e32 v73, v0
	v_mov_b32_e32 v74, v0
	v_mov_b32_e32 v75, v0
	v_mov_b32_e32 v76, v0
	v_mov_b32_e32 v77, v0
	v_mov_b32_e32 v78, v0
	v_mov_b32_e32 v79, v0
	v_mov_b32_e32 v88, v0
	v_mov_b32_e32 v89, v0
	v_mov_b32_e32 v90, v0
	v_mov_b32_e32 v91, v0
	v_mov_b32_e32 v92, v0
	v_mov_b32_e32 v93, v0
	v_mov_b32_e32 v94, v0
	v_mov_b32_e32 v95, v0
	v_mov_b32_e32 v104, v0
	v_mov_b32_e32 v105, v0
	v_mov_b32_e32 v106, v0
	v_mov_b32_e32 v107, v0
	v_mov_b32_e32 v108, v0
	v_mov_b32_e32 v109, v0
	v_mov_b32_e32 v110, v0
	v_mov_b32_e32 v111, v0
	v_mov_b32_e32 v120, v0
	v_mov_b32_e32 v121, v0
	v_mov_b32_e32 v122, v0
	v_mov_b32_e32 v123, v0
	v_mov_b32_e32 v124, v0
	v_mov_b32_e32 v125, v0
	v_mov_b32_e32 v126, v0
	v_mov_b32_e32 v127, v0
	.p2align 6

; template <class GEO, class Epi>
; __device__ __forceinline__ void gemm_phase(LAS unsigned char* lds, const Gemm g, const StaticOrder& S, const Epi& E) {
;     ...
; #pragma unroll
;     for (int a = 0; a < 2; ++a)
; #pragma unroll
;         for (int b = 0; b < 2; ++b)
; #pragma unroll
;             for (int m = 0; m < 4; ++m)
; #pragma unroll
;                 for (int n = 0; n < 2; ++n) acc[a][b][m][n] = (f32x4){0.f, 0.f, 0.f, 0.f};
;     ...
;         const bool has_next = S.next(ui + 1, nxt);
;         const char* nA = has_next ? PG8_APTR(nxt) : cA; const char* nB = has_next ? PG8_BPTR(nxt) : cB;
; #pragma nounroll
;         for (int t = 0; t < nt; t += 2) {
;             const bool last = (t == nt - 2);
;             const char* a1 = cA + (size_t)(t + 1) * kstep;
;             const char* a2 = last ? nA : cA + (size_t)(t + 2) * kstep; const char* b2 = last ? nB : cB + (size_t)(t + 2) * kstep;
;             const char* a3 = a2 + kstep; const char* b3 = b2 + kstep;
.LBB0_988:
	s_ashr_i32 s47, s46, 31
	s_lshl_b64 s[38:39], s[46:47], 19
	s_add_u32 s48, s16, s38
	s_addc_u32 s49, s17, s39
	s_and_b64 s[38:39], s[44:45], exec
	s_cselect_b32 s15, s49, s53
	s_cselect_b32 s23, s48, s52
	s_ashr_i32 s38, s46, 5
	s_and_b32 s28, s64, 0x3fffffff
	s_ashr_i32 s39, s38, 31
	s_lshl_b64 s[38:39], s[38:39], 11
	s_lshl_b64 s[50:51], s[28:29], 21
	s_add_u32 s28, s24, s50
	s_addc_u32 s47, s25, s51
	s_add_u32 s50, s28, s38
	s_addc_u32 s51, s47, s39
	s_and_b64 s[38:39], s[44:45], exec
	s_cselect_b32 s28, s51, s55
	s_cselect_b32 s47, s50, s54
	s_add_u32 s52, s52, 0x40080
	s_addc_u32 s53, s53, 0
	s_add_u32 s65, s54, 0x100
	v_mov_b32_e32 v0, 0
	s_addc_u32 s66, s55, 0
	s_mov_b32 s67, -2
	s_waitcnt lgkmcnt(0)
	v_mov_b32_e32 v1, v0
	v_mov_b32_e32 v2, v0
	v_mov_b32_e32 v3, v0
	v_mov_b32_e32 v4, v0
	v_mov_b32_e32 v5, v0
	v_mov_b32_e32 v6, v0
	v_mov_b32_e32 v7, v0
	v_mov_b32_e32 v16, v0
	v_mov_b32_e32 v17, v0
	v_mov_b32_e32 v18, v0
	v_mov_b32_e32 v19, v0
	v_mov_b32_e32 v20, v0
	v_mov_b32_e32 v21, v0
	v_mov_b32_e32 v22, v0
	v_mov_b32_e32 v23, v0
	v_mov_b32_e32 v32, v0
	v_mov_b32_e32 v33, v0
	v_mov_b32_e32 v34, v0
	v_mov_b32_e32 v35, v0
	v_mov_b32_e32 v36, v0
	v_mov_b32_e32 v37, v0
	v_mov_b32_e32 v38, v0
	v_mov_b32_e32 v39, v0
	v_mov_b32_e32 v48, v0
	v_mov_b32_e32 v49, v0
	v_mov_b32_e32 v50, v0
	v_mov_b32_e32 v51, v0
	v_mov_b32_e32 v52, v0
	v_mov_b32_e32 v53, v0
	v_mov_b32_e32 v54, v0
	v_mov_b32_e32 v55, v0
	v_mov_b32_e32 v8, v0
	v_mov_b32_e32 v9, v0
	v_mov_b32_e32 v10, v0
	v_mov_b32_e32 v11, v0
	v_mov_b32_e32 v12, v0
	v_mov_b32_e32 v13, v0
	v_mov_b32_e32 v14, v0
	v_mov_b32_e32 v15, v0
	v_mov_b32_e32 v24, v0
	v_mov_b32_e32 v25, v0
	v_mov_b32_e32 v26, v0
	v_mov_b32_e32 v27, v0
	v_mov_b32_e32 v28, v0
	v_mov_b32_e32 v29, v0
	v_mov_b32_e32 v30, v0
	v_mov_b32_e32 v31, v0
	v_mov_b32_e32 v40, v0
	v_mov_b32_e32 v41, v0
	v_mov_b32_e32 v42, v0
	v_mov_b32_e32 v43, v0
	v_mov_b32_e32 v44, v0
	v_mov_b32_e32 v45, v0
	v_mov_b32_e32 v46, v0
	v_mov_b32_e32 v47, v0
	v_mov_b32_e32 v56, v0
	v_mov_b32_e32 v57, v0
	v_mov_b32_e32 v58, v0
	v_mov_b32_e32 v59, v0
	v_mov_b32_e32 v60, v0
	v_mov_b32_e32 v61, v0
	v_mov_b32_e32 v62, v0
	v_mov_b32_e32 v63, v0
	v_mov_b32_e32 v64, v0
	v_mov_b32_e32 v65, v0
	v_mov_b32_e32 v66, v0
	v_mov_b32_e32 v67, v0
	v_mov_b32_e32 v68, v0
	v_mov_b32_e32 v69, v0
	v_mov_b32_e32 v70, v0
	v_mov_b32_e32 v71, v0
	v_mov_b32_e32 v80, v0
	v_mov_b32_e32 v81, v0
	v_mov_b32_e32 v82, v0
	v_mov_b32_e32 v83, v0
	v_mov_b32_e32 v84, v0
	v_mov_b32_e32 v85, v0
	v_mov_b32_e32 v86, v0
	v_mov_b32_e32 v87, v0
	v_mov_b32_e32 v96, v0
	v_mov_b32_e32 v97, v0
	v_mov_b32_e32 v98, v0
	v_mov_b32_e32 v99, v0
	v_mov_b32_e32 v100, v0
	v_mov_b32_e32 v101, v0
	v_mov_b32_e32 v102, v0
	v_mov_b32_e32 v103, v0
	v_mov_b32_e32 v112, v0
	v_mov_b32_e32 v113, v0
	v_mov_b32_e32 v114, v0
	v_mov_b32_e32 v115, v0
	v_mov_b32_e32 v116, v0
	v_mov_b32_e32 v117, v0
	v_mov_b32_e32 v118, v0
	v_mov_b32_e32 v119, v0
	v_mov_b32_e32 v72, v0
	v_mov_b32_e32 v73, v0
	v_mov_b32_e32 v74, v0
	v_mov_b32_e32 v75, v0
	v_mov_b32_e32 v76, v0
	v_mov_b32_e32 v77, v0
	v_mov_b32_e32 v78, v0
	v_mov_b32_e32 v79, v0
	v_mov_b32_e32 v88, v0
	v_mov_b32_e32 v89, v0
	v_mov_b32_e32 v90, v0
	v_mov_b32_e32 v91, v0
	v_mov_b32_e32 v92, v0
	v_mov_b32_e32 v93, v0
	v_mov_b32_e32 v94, v0
	v_mov_b32_e32 v95, v0
	v_mov_b32_e32 v104, v0
	v_mov_b32_e32 v105, v0
	v_mov_b32_e32 v106, v0
	v_mov_b32_e32 v107, v0
	v_mov_b32_e32 v108, v0
	v_mov_b32_e32 v109, v0
	v_mov_b32_e32 v110, v0
	v_mov_b32_e32 v111, v0
	v_mov_b32_e32 v120, v0
	v_mov_b32_e32 v121, v0
	v_mov_b32_e32 v122, v0
	v_mov_b32_e32 v123, v0
	v_mov_b32_e32 v124, v0
	v_mov_b32_e32 v125, v0
	v_mov_b32_e32 v126, v0
	v_mov_b32_e32 v127, v0
	.p2align 6

; template <class GEO, class Epi>
; __device__ __forceinline__ void gemm_phase(LAS unsigned char* lds, const Gemm g, const StaticOrder& S, const Epi& E) {
;     ...
; #pragma unroll
;     for (int a = 0; a < 2; ++a)
; #pragma unroll
;         for (int b = 0; b < 2; ++b)
; #pragma unroll
;             for (int m = 0; m < 4; ++m)
; #pragma unroll
;                 for (int n = 0; n < 2; ++n) acc[a][b][m][n] = (f32x4){0.f, 0.f, 0.f, 0.f};
;     ...
;         const bool has_next = S.next(ui + 1, nxt);
;         const char* nA = has_next ? PG8_APTR(nxt) : cA; const char* nB = has_next ? PG8_BPTR(nxt) : cB;
; #pragma nounroll
;         for (int t = 0; t < nt; t += 2) {
;             const bool last = (t == nt - 2);
;             const char* a1 = cA + (size_t)(t + 1) * kstep;
;             const char* a2 = last ? nA : cA + (size_t)(t + 2) * kstep; const char* b2 = last ? nB : cB + (size_t)(t + 2) * kstep;
;             const char* a3 = a2 + kstep; const char* b3 = b2 + kstep;
.LBB0_1074:
	s_ashr_i32 s31, s30, 31
	s_lshl_b64 s[34:35], s[30:31], 19
	s_add_u32 s34, s26, s34
	s_addc_u32 s35, s27, s35
	s_and_b64 s[38:39], s[40:41], exec
	s_cselect_b32 s21, s35, s23
	s_cselect_b32 s31, s34, s22
	s_and_b32 s14, s36, 0x3fffffff
	s_lshl_b64 s[38:39], s[14:15], 19
	s_add_u32 s42, s76, s38
	s_addc_u32 s43, s77, s39
	s_and_b64 s[38:39], s[40:41], exec
	s_cselect_b32 s14, s43, s45
	s_cselect_b32 s48, s42, s44
	s_add_u32 s22, s22, 0x40080
	s_addc_u32 s23, s23, 0
	s_add_u32 s49, s44, 0x100
	v_mov_b32_e32 v0, 0
	s_addc_u32 s50, s45, 0
	s_mov_b32 s51, -2
	v_mov_b32_e32 v1, v0
	v_mov_b32_e32 v2, v0
	v_mov_b32_e32 v3, v0
	v_mov_b32_e32 v4, v0
	v_mov_b32_e32 v5, v0
	v_mov_b32_e32 v6, v0
	v_mov_b32_e32 v7, v0
	v_mov_b32_e32 v16, v0
	v_mov_b32_e32 v17, v0
	v_mov_b32_e32 v18, v0
	v_mov_b32_e32 v19, v0
	v_mov_b32_e32 v20, v0
	v_mov_b32_e32 v21, v0
	v_mov_b32_e32 v22, v0
	v_mov_b32_e32 v23, v0
	v_mov_b32_e32 v32, v0
	v_mov_b32_e32 v33, v0
	v_mov_b32_e32 v34, v0
	v_mov_b32_e32 v35, v0
	v_mov_b32_e32 v36, v0
	v_mov_b32_e32 v37, v0
	v_mov_b32_e32 v38, v0
	v_mov_b32_e32 v39, v0
	v_mov_b32_e32 v48, v0
	v_mov_b32_e32 v49, v0
	v_mov_b32_e32 v50, v0
	v_mov_b32_e32 v51, v0
	v_mov_b32_e32 v52, v0
	v_mov_b32_e32 v53, v0
	v_mov_b32_e32 v54, v0
	v_mov_b32_e32 v55, v0
	v_mov_b32_e32 v8, v0
	v_mov_b32_e32 v9, v0
	v_mov_b32_e32 v10, v0
	v_mov_b32_e32 v11, v0
	v_mov_b32_e32 v12, v0
	v_mov_b32_e32 v13, v0
	v_mov_b32_e32 v14, v0
	v_mov_b32_e32 v15, v0
	v_mov_b32_e32 v24, v0
	v_mov_b32_e32 v25, v0
	v_mov_b32_e32 v26, v0
	v_mov_b32_e32 v27, v0
	v_mov_b32_e32 v28, v0
	v_mov_b32_e32 v29, v0
	v_mov_b32_e32 v30, v0
	v_mov_b32_e32 v31, v0
	v_mov_b32_e32 v40, v0
	v_mov_b32_e32 v41, v0
	v_mov_b32_e32 v42, v0
	v_mov_b32_e32 v43, v0
	v_mov_b32_e32 v44, v0
	v_mov_b32_e32 v45, v0
	v_mov_b32_e32 v46, v0
	v_mov_b32_e32 v47, v0
	v_mov_b32_e32 v56, v0
	v_mov_b32_e32 v57, v0
	v_mov_b32_e32 v58, v0
	v_mov_b32_e32 v59, v0
	v_mov_b32_e32 v60, v0
	v_mov_b32_e32 v61, v0
	v_mov_b32_e32 v62, v0
	v_mov_b32_e32 v63, v0
	v_mov_b32_e32 v64, v0
	v_mov_b32_e32 v65, v0
	v_mov_b32_e32 v66, v0
	v_mov_b32_e32 v67, v0
	v_mov_b32_e32 v68, v0
	v_mov_b32_e32 v69, v0
	v_mov_b32_e32 v70, v0
	v_mov_b32_e32 v71, v0
	v_mov_b32_e32 v80, v0
	v_mov_b32_e32 v81, v0
	v_mov_b32_e32 v82, v0
	v_mov_b32_e32 v83, v0
	v_mov_b32_e32 v84, v0
	v_mov_b32_e32 v85, v0
	v_mov_b32_e32 v86, v0
	v_mov_b32_e32 v87, v0
	v_mov_b32_e32 v96, v0
	v_mov_b32_e32 v97, v0
	v_mov_b32_e32 v98, v0
	v_mov_b32_e32 v99, v0
	v_mov_b32_e32 v100, v0
	v_mov_b32_e32 v101, v0
	v_mov_b32_e32 v102, v0
	v_mov_b32_e32 v103, v0
	v_mov_b32_e32 v112, v0
	v_mov_b32_e32 v113, v0
	v_mov_b32_e32 v114, v0
	v_mov_b32_e32 v115, v0
	v_mov_b32_e32 v116, v0
	v_mov_b32_e32 v117, v0
	v_mov_b32_e32 v118, v0
	v_mov_b32_e32 v119, v0
	v_mov_b32_e32 v72, v0
	v_mov_b32_e32 v73, v0
	v_mov_b32_e32 v74, v0
	v_mov_b32_e32 v75, v0
	v_mov_b32_e32 v76, v0
	v_mov_b32_e32 v77, v0
	v_mov_b32_e32 v78, v0
	v_mov_b32_e32 v79, v0
	v_mov_b32_e32 v88, v0
	v_mov_b32_e32 v89, v0
	v_mov_b32_e32 v90, v0
	v_mov_b32_e32 v91, v0
	v_mov_b32_e32 v92, v0
	v_mov_b32_e32 v93, v0
	v_mov_b32_e32 v94, v0
	v_mov_b32_e32 v95, v0
	v_mov_b32_e32 v104, v0
	v_mov_b32_e32 v105, v0
	v_mov_b32_e32 v106, v0
	v_mov_b32_e32 v107, v0
	v_mov_b32_e32 v108, v0
	v_mov_b32_e32 v109, v0
	v_mov_b32_e32 v110, v0
	v_mov_b32_e32 v111, v0
	v_mov_b32_e32 v120, v0
	v_mov_b32_e32 v121, v0
	v_mov_b32_e32 v122, v0
	v_mov_b32_e32 v123, v0
	v_mov_b32_e32 v124, v0
	v_mov_b32_e32 v125, v0
	v_mov_b32_e32 v126, v0
	v_mov_b32_e32 v127, v0
	.p2align 6

; template <class GEO, class Epi>
; __device__ __forceinline__ void gemm_phase(LAS unsigned char* lds, const Gemm g, const StaticOrder& S, const Epi& E) {
;     ...
; #pragma unroll
;     for (int a = 0; a < 2; ++a)
; #pragma unroll
;         for (int b = 0; b < 2; ++b)
; #pragma unroll
;             for (int m = 0; m < 4; ++m)
; #pragma unroll
;                 for (int n = 0; n < 2; ++n) acc[a][b][m][n] = (f32x4){0.f, 0.f, 0.f, 0.f};
;     ...
;         const bool has_next = S.next(ui + 1, nxt);
;         const char* nA = has_next ? PG8_APTR(nxt) : cA; const char* nB = has_next ? PG8_BPTR(nxt) : cB;
; #pragma nounroll
;         for (int t = 0; t < nt; t += 2) {
;             const bool last = (t == nt - 2);
;             const char* a1 = cA + (size_t)(t + 1) * kstep;
;             const char* a2 = last ? nA : cA + (size_t)(t + 2) * kstep; const char* b2 = last ? nB : cB + (size_t)(t + 2) * kstep;
;             const char* a3 = a2 + kstep; const char* b3 = b2 + kstep;
.LBB0_1147:
	s_ashr_i32 s15, s14, 31
	s_lshl_b64 s[16:17], s[14:15], 21
	s_add_u32 s16, s96, s16
	s_addc_u32 s17, s97, s17
	s_and_b64 s[18:19], s[0:1], exec
	s_cselect_b32 s15, s17, s23
	s_cselect_b32 s42, s16, s22
	s_and_b32 s4, s40, 0x3fffffff
	s_lshl_b64 s[18:19], s[4:5], 21
	s_add_u32 s18, s70, s18
	s_addc_u32 s19, s71, s19
	s_and_b64 s[28:29], s[0:1], exec
	s_cselect_b32 s4, s19, s25
	s_cselect_b32 s43, s18, s24
	s_add_u32 s22, s22, 0x100080
	s_addc_u32 s23, s23, 0
	s_add_u32 s44, s24, 0x100
	v_mov_b32_e32 v0, 0
	s_addc_u32 s45, s25, 0
	s_mov_b32 s46, -2
	v_mov_b32_e32 v1, v0
	v_mov_b32_e32 v2, v0
	v_mov_b32_e32 v3, v0
	v_mov_b32_e32 v4, v0
	v_mov_b32_e32 v5, v0
	v_mov_b32_e32 v6, v0
	v_mov_b32_e32 v7, v0
	v_mov_b32_e32 v16, v0
	v_mov_b32_e32 v17, v0
	v_mov_b32_e32 v18, v0
	v_mov_b32_e32 v19, v0
	v_mov_b32_e32 v20, v0
	v_mov_b32_e32 v21, v0
	v_mov_b32_e32 v22, v0
	v_mov_b32_e32 v23, v0
	v_mov_b32_e32 v32, v0
	v_mov_b32_e32 v33, v0
	v_mov_b32_e32 v34, v0
	v_mov_b32_e32 v35, v0
	v_mov_b32_e32 v36, v0
	v_mov_b32_e32 v37, v0
	v_mov_b32_e32 v38, v0
	v_mov_b32_e32 v39, v0
	v_mov_b32_e32 v48, v0
	v_mov_b32_e32 v49, v0
	v_mov_b32_e32 v50, v0
	v_mov_b32_e32 v51, v0
	v_mov_b32_e32 v52, v0
	v_mov_b32_e32 v53, v0
	v_mov_b32_e32 v54, v0
	v_mov_b32_e32 v55, v0
	v_mov_b32_e32 v8, v0
	v_mov_b32_e32 v9, v0
	v_mov_b32_e32 v10, v0
	v_mov_b32_e32 v11, v0
	v_mov_b32_e32 v12, v0
	v_mov_b32_e32 v13, v0
	v_mov_b32_e32 v14, v0
	v_mov_b32_e32 v15, v0
	v_mov_b32_e32 v24, v0
	v_mov_b32_e32 v25, v0
	v_mov_b32_e32 v26, v0
	v_mov_b32_e32 v27, v0
	v_mov_b32_e32 v28, v0
	v_mov_b32_e32 v29, v0
	v_mov_b32_e32 v30, v0
	v_mov_b32_e32 v31, v0
	v_mov_b32_e32 v40, v0
	v_mov_b32_e32 v41, v0
	v_mov_b32_e32 v42, v0
	v_mov_b32_e32 v43, v0
	v_mov_b32_e32 v44, v0
	v_mov_b32_e32 v45, v0
	v_mov_b32_e32 v46, v0
	v_mov_b32_e32 v47, v0
	v_mov_b32_e32 v56, v0
	v_mov_b32_e32 v57, v0
	v_mov_b32_e32 v58, v0
	v_mov_b32_e32 v59, v0
	v_mov_b32_e32 v60, v0
	v_mov_b32_e32 v61, v0
	v_mov_b32_e32 v62, v0
	v_mov_b32_e32 v63, v0
	v_mov_b32_e32 v64, v0
	v_mov_b32_e32 v65, v0
	v_mov_b32_e32 v66, v0
	v_mov_b32_e32 v67, v0
	v_mov_b32_e32 v68, v0
	v_mov_b32_e32 v69, v0
	v_mov_b32_e32 v70, v0
	v_mov_b32_e32 v71, v0
	v_mov_b32_e32 v80, v0
	v_mov_b32_e32 v81, v0
	v_mov_b32_e32 v82, v0
	v_mov_b32_e32 v83, v0
	v_mov_b32_e32 v84, v0
	v_mov_b32_e32 v85, v0
	v_mov_b32_e32 v86, v0
	v_mov_b32_e32 v87, v0
	v_mov_b32_e32 v96, v0
	v_mov_b32_e32 v97, v0
	v_mov_b32_e32 v98, v0
	v_mov_b32_e32 v99, v0
	v_mov_b32_e32 v100, v0
	v_mov_b32_e32 v101, v0
	v_mov_b32_e32 v102, v0
	v_mov_b32_e32 v103, v0
	v_mov_b32_e32 v112, v0
	v_mov_b32_e32 v113, v0
	v_mov_b32_e32 v114, v0
	v_mov_b32_e32 v115, v0
	v_mov_b32_e32 v116, v0
	v_mov_b32_e32 v117, v0
	v_mov_b32_e32 v118, v0
	v_mov_b32_e32 v119, v0
	v_mov_b32_e32 v72, v0
	v_mov_b32_e32 v73, v0
	v_mov_b32_e32 v74, v0
	v_mov_b32_e32 v75, v0
	v_mov_b32_e32 v76, v0
	v_mov_b32_e32 v77, v0
	v_mov_b32_e32 v78, v0
	v_mov_b32_e32 v79, v0
	v_mov_b32_e32 v88, v0
	v_mov_b32_e32 v89, v0
	v_mov_b32_e32 v90, v0
	v_mov_b32_e32 v91, v0
	v_mov_b32_e32 v92, v0
	v_mov_b32_e32 v93, v0
	v_mov_b32_e32 v94, v0
	v_mov_b32_e32 v95, v0
	v_mov_b32_e32 v104, v0
	v_mov_b32_e32 v105, v0
	v_mov_b32_e32 v106, v0
	v_mov_b32_e32 v107, v0
	v_mov_b32_e32 v108, v0
	v_mov_b32_e32 v109, v0
	v_mov_b32_e32 v110, v0
	v_mov_b32_e32 v111, v0
	v_mov_b32_e32 v120, v0
	v_mov_b32_e32 v121, v0
	v_mov_b32_e32 v122, v0
	v_mov_b32_e32 v123, v0
	v_mov_b32_e32 v124, v0
	v_mov_b32_e32 v125, v0
	v_mov_b32_e32 v126, v0
	v_mov_b32_e32 v127, v0
	.p2align 6
